# speedup vs baseline: 1.0011x; 1.0011x over previous
; DI int tid_() { int t = threadIdx.x; asm volatile("" : "+v"(t)); return t; }
; DI int bid_() { int b = blockIdx.x; asm volatile("" : "+s"(b)); return b; }
; DI void phase_final_norm(float* x, const float* g, int rows) {
;   const int wid = tid_() >> 6, lane = tid_() & 63;
;   for (int row = bid_() * 8 + wid; row < rows; row += gridDim.x * 8) {
;     float* xr = x + (size_t)row * 1024;
;     float4 v[4]; float ss = 0.f;
; #pragma unroll
;     for (int i = 0; i < 4; ++i) { float4 t = *reinterpret_cast<const float4*>(xr + i * 256 + lane * 4); v[i] = t; ss += t.x * t.x + t.y * t.y + t.z * t.z + t.w * t.w; }
;     ss = wave_sum_l(ss, lane);
;     const float r = rsqrtf(ss * (1.f / 1024.f) + EPS);
; #pragma unroll
;     for (int i = 0; i < 4; ++i) { const float4 gg = *reinterpret_cast<const float4*>(g + i * 256 + lane * 4);
;       float4 o = make_float4(v[i].x * r * gg.x, v[i].y * r * gg.y, v[i].z * r * gg.z, v[i].w * r * gg.w);
;       *reinterpret_cast<float4*>(xr + i * 256 + lane * 4) = o; }
;   }
; }
.LBB0_32:
	v_ashrrev_i32_e32 v1, 31, v0
	v_lshlrev_b64 v[8:9], 12, v[0:1]
	v_lshl_add_u64 v[28:29], v[4:5], 0, v[8:9]
	global_load_dwordx4 v[8:11], v[28:29], off nt
	global_load_dwordx4 v[12:15], v[28:29], off offset:1024 nt
	global_load_dwordx4 v[16:19], v[28:29], off offset:2048 nt
	global_load_dwordx4 v[20:23], v[28:29], off offset:3072 nt
	v_add_u32_e32 v0, s99, v0
	s_mov_b32 s2, 0xbfff
	s_waitcnt vmcnt(3)
	v_mov_b32_e32 v32, v9
	s_waitcnt vmcnt(2)
	v_mov_b32_e32 v33, v13
	v_mov_b32_e32 v30, v8
	v_mov_b32_e32 v31, v12
	s_waitcnt vmcnt(1)
	v_mov_b32_e32 v40, v17
	s_waitcnt vmcnt(0)
	v_mov_b32_e32 v41, v21
	v_pk_mul_f32 v[32:33], v[32:33], v[32:33]
	v_mov_b32_e32 v34, v10
	v_mov_b32_e32 v35, v14
	v_mov_b32_e32 v38, v16
	v_mov_b32_e32 v39, v20
	v_pk_mul_f32 v[40:41], v[40:41], v[40:41]
	v_pk_fma_f32 v[30:31], v[30:31], v[30:31], v[32:33]
	v_mov_b32_e32 v36, v11
	v_mov_b32_e32 v37, v15
	v_mov_b32_e32 v42, v18
	v_mov_b32_e32 v43, v22
	v_pk_fma_f32 v[32:33], v[38:39], v[38:39], v[40:41]
	v_pk_fma_f32 v[30:31], v[34:35], v[34:35], v[30:31]
	v_mov_b32_e32 v44, v19
	v_mov_b32_e32 v45, v23
	v_pk_fma_f32 v[32:33], v[42:43], v[42:43], v[32:33]
	v_pk_fma_f32 v[30:31], v[36:37], v[36:37], v[30:31]
	v_pk_fma_f32 v[32:33], v[44:45], v[44:45], v[32:33]
	v_add_f32_e32 v1, v30, v31
	v_add_f32_e32 v1, v1, v32
	v_add_f32_e32 v1, v1, v33
	s_nop 1
	v_add_f32_dpp v1, v1, v1 quad_perm:[1,0,3,2] row_mask:0xf bank_mask:0xf bound_ctrl:1
	s_nop 1
	v_add_f32_dpp v1, v1, v1 quad_perm:[2,3,0,1] row_mask:0xf bank_mask:0xf bound_ctrl:1
	s_nop 1
	v_add_f32_dpp v1, v1, v1 row_half_mirror row_mask:0xf bank_mask:0xf bound_ctrl:1
	s_nop 1
	v_add_f32_dpp v1, v1, v1 row_mirror row_mask:0xf bank_mask:0xf bound_ctrl:1
	ds_bpermute_b32 v30, v6, v1
	s_waitcnt lgkmcnt(0)
	v_add_f32_e32 v1, v1, v30
	ds_bpermute_b32 v30, v7, v1
	s_waitcnt lgkmcnt(0)
	v_add_f32_e32 v1, v1, v30
	v_fmamk_f32 v1, v1, 0x3a800000, v233
	v_mul_f32_e32 v30, 0x4b800000, v1
	v_cmp_gt_f32_e32 vcc, s94, v1
	s_nop 1
	v_cndmask_b32_e32 v1, v1, v30, vcc
	v_rsq_f32_e32 v1, v1
	s_nop 0
	v_mul_f32_e32 v30, 0x45800000, v1
	v_cndmask_b32_e32 v30, v1, v30, vcc
	v_pk_mul_f32 v[8:9], v[8:9], v[30:31] op_sel_hi:[1,0]
	v_pk_mul_f32 v[10:11], v[10:11], v[30:31] op_sel_hi:[1,0]
	v_pk_mul_f32 v[8:9], v[48:49], v[8:9]
	v_pk_mul_f32 v[10:11], v[50:51], v[10:11]
	global_store_dwordx4 v[28:29], v[8:11], off nt
	v_pk_mul_f32 v[12:13], v[12:13], v[30:31] op_sel_hi:[1,0]
	v_pk_mul_f32 v[14:15], v[14:15], v[30:31] op_sel_hi:[1,0]
	v_cmp_lt_i32_e32 vcc, s2, v0
	s_or_b64 s[36:37], vcc, s[36:37]
	v_pk_mul_f32 v[12:13], v[52:53], v[12:13]
	v_pk_mul_f32 v[14:15], v[54:55], v[14:15]
	global_store_dwordx4 v[28:29], v[12:15], off offset:1024 nt
	v_pk_mul_f32 v[16:17], v[16:17], v[30:31] op_sel_hi:[1,0]
	v_pk_mul_f32 v[18:19], v[18:19], v[30:31] op_sel_hi:[1,0]
	v_pk_mul_f32 v[16:17], v[16:17], v[56:57]
	v_pk_mul_f32 v[18:19], v[18:19], v[58:59]
	global_store_dwordx4 v[28:29], v[16:19], off offset:2048 nt
	v_pk_mul_f32 v[20:21], v[20:21], v[30:31] op_sel_hi:[1,0]
	v_pk_mul_f32 v[22:23], v[22:23], v[30:31] op_sel_hi:[1,0]
	v_pk_mul_f32 v[20:21], v[20:21], v[60:61]
	v_pk_mul_f32 v[22:23], v[22:23], v[62:63]
	global_store_dwordx4 v[28:29], v[20:23], off offset:3072 nt
	s_andn2_b64 exec, exec, s[36:37]
	s_cbranch_execnz .LBB0_32
